# grid barrier: non-master workgroups poll the top-level generation word directly (one relay hop less)
# speedup vs baseline: 1.0156x; 1.0156x over previous
; __device__ __forceinline__ unsigned xb_ld(unsigned* p)              { return __hip_atomic_load(p, __ATOMIC_RELAXED, __HIP_MEMORY_SCOPE_AGENT); }
; __device__ __forceinline__ unsigned xb_add(unsigned* p, unsigned v) { return __hip_atomic_fetch_add(p, v, __ATOMIC_RELAXED, __HIP_MEMORY_SCOPE_AGENT); }
; #define XB_SPIN(cond, bar) do { unsigned _sp = 0; while (cond) { __builtin_amdgcn_s_sleep(1); \
;     if ((++_sp & 255u) == 0u) { if (xb_ld(&(bar)[XB_TMO])) break; if (_sp > XB_SPIN_CAP) { atomicAdd(&(bar)[XB_TMO], 1u); break; } } } } while (0)
; __device__ __forceinline__ void grid_barrier(const XcdBarrier& b) {
;     asm volatile("s_waitcnt vmcnt(0)" ::: "memory");
;     __syncthreads();
;     if (threadIdx.x == 0) {
;         unsigned* bar = b.bar;
;         __builtin_amdgcn_s_waitcnt(0);
;         unsigned nloc = b.st[0], nx = b.st[1];
;         if (nloc == 0u) { xcd_barrier_complete(bar, b.x, nloc, nx); b.st[0] = nloc; b.st[1] = nx; }
;         const unsigned old = xb_add(&bar[XB_XSUB(b.x)], 1u);
;         const unsigned gen = old / nloc;
;         if (old + 1u == (gen + 1u) * nloc) {
;             __builtin_amdgcn_fence(__ATOMIC_RELEASE, "agent");
;             asm volatile("s_waitcnt vmcnt(0)" ::: "memory");
;             const unsigned og = xb_add(&bar[XB_TOP], 1u);
;             const unsigned tg = og / nx;
;             if (og + 1u == (tg + 1u) * nx) xb_add(&bar[XB_TOPGEN], 1u);
;             else XB_SPIN(xb_ld(&bar[XB_TOPGEN]) == tg, bar);
;             __builtin_amdgcn_fence(__ATOMIC_ACQUIRE, "agent");
;             xb_add(&bar[XB_XGEN(b.x)], 1u);
;             asm volatile("s_waitcnt vmcnt(0)" ::: "memory");
;         } else {
;             XB_SPIN(xb_ld(&bar[XB_XGEN(b.x)]) == gen, bar);
;             __builtin_amdgcn_fence(__ATOMIC_ACQUIRE, "agent");
;             asm volatile("s_waitcnt vmcnt(0)" ::: "memory");
;         }
.LBB0_319:
	global_atomic_add v4, v[134:135], v204, off sc0
	v_cvt_f32_u32_e32 v0, v3
	v_sub_u32_e32 v5, 0, v3
	v_rcp_iflag_f32_e32 v0, v0
	s_nop 0
	v_mul_f32_e32 v0, 0x4f7ffffe, v0
	v_cvt_u32_f32_e32 v0, v0
	v_mul_lo_u32 v5, v5, v0
	v_mul_hi_u32 v5, v0, v5
	v_add_u32_e32 v0, v0, v5
	s_waitcnt vmcnt(0)
	v_mul_hi_u32 v0, v4, v0
	v_mul_lo_u32 v5, v0, v3
	v_sub_u32_e32 v5, v4, v5
	v_add_u32_e32 v6, 1, v0
	v_cmp_ge_u32_e32 vcc, v5, v3
	v_add_u32_e32 v4, 1, v4
	s_nop 0
	v_cndmask_b32_e32 v0, v0, v6, vcc
	v_sub_u32_e32 v6, v5, v3
	v_cndmask_b32_e32 v5, v5, v6, vcc
	v_add_u32_e32 v6, 1, v0
	v_cmp_ge_u32_e32 vcc, v5, v3
	s_nop 1
	v_cndmask_b32_e32 v0, v0, v6, vcc
	v_mul_lo_u32 v5, v3, v0
	v_add_u32_e32 v3, v5, v3
	v_cmp_ne_u32_e32 vcc, v4, v3
	s_and_saveexec_b64 s[6:7], vcc
	s_xor_b64 s[12:13], exec, s[6:7]
	s_cbranch_execz .LBB0_333
	s_waitcnt lgkmcnt(0)
	v_readlane_b32 s6, v254, 14
	v_readlane_b32 s7, v254, 15
	s_nop 4
	global_load_dword v2, v1, s[6:7] sc1
	s_waitcnt vmcnt(0)
	v_cmp_eq_u32_e32 vcc, v2, v0
	s_and_saveexec_b64 s[14:15], vcc
	s_cbranch_execz .LBB0_332
	s_mov_b32 s2, 1
	s_mov_b64 s[16:17], 0
	s_branch .LBB0_323

; __device__ __forceinline__ unsigned xb_ld(unsigned* p)              { return __hip_atomic_load(p, __ATOMIC_RELAXED, __HIP_MEMORY_SCOPE_AGENT); }
; #define XB_SPIN(cond, bar) do { unsigned _sp = 0; while (cond) { __builtin_amdgcn_s_sleep(1); \
;     if ((++_sp & 255u) == 0u) { if (xb_ld(&(bar)[XB_TMO])) break; if (_sp > XB_SPIN_CAP) { atomicAdd(&(bar)[XB_TMO], 1u); break; } } } } while (0)
; __device__ __forceinline__ void grid_barrier(const XcdBarrier& b) {
;     ...
;             XB_SPIN(xb_ld(&bar[XB_XGEN(b.x)]) == gen, bar);
.LBB0_327:
	v_readlane_b32 s6, v254, 14
	v_readlane_b32 s7, v254, 15
	s_nop 4
	global_load_dword v2, v1, s[6:7] sc1
	s_add_i32 s2, s2, 1
	s_mov_b64 s[22:23], -1
	s_waitcnt vmcnt(0)
	v_cmp_ne_u32_e32 vcc, v2, v0
	s_orn2_b64 s[20:21], vcc, exec
	s_branch .LBB0_322

; __device__ __forceinline__ unsigned xb_ld(unsigned* p)              { return __hip_atomic_load(p, __ATOMIC_RELAXED, __HIP_MEMORY_SCOPE_AGENT); }
; __device__ __forceinline__ unsigned xb_add(unsigned* p, unsigned v) { return __hip_atomic_fetch_add(p, v, __ATOMIC_RELAXED, __HIP_MEMORY_SCOPE_AGENT); }
; #define XB_SPIN(cond, bar) do { unsigned _sp = 0; while (cond) { __builtin_amdgcn_s_sleep(1); \
;     if ((++_sp & 255u) == 0u) { if (xb_ld(&(bar)[XB_TMO])) break; if (_sp > XB_SPIN_CAP) { atomicAdd(&(bar)[XB_TMO], 1u); break; } } } } while (0)
; __device__ __forceinline__ void grid_barrier(const XcdBarrier& b) {
;     asm volatile("s_waitcnt vmcnt(0)" ::: "memory");
;     __syncthreads();
;     if (threadIdx.x == 0) {
;         unsigned* bar = b.bar;
;         __builtin_amdgcn_s_waitcnt(0);
;         unsigned nloc = b.st[0], nx = b.st[1];
;         if (nloc == 0u) { xcd_barrier_complete(bar, b.x, nloc, nx); b.st[0] = nloc; b.st[1] = nx; }
;         const unsigned old = xb_add(&bar[XB_XSUB(b.x)], 1u);
;         const unsigned gen = old / nloc;
;         if (old + 1u == (gen + 1u) * nloc) {
;             __builtin_amdgcn_fence(__ATOMIC_RELEASE, "agent");
;             asm volatile("s_waitcnt vmcnt(0)" ::: "memory");
;             const unsigned og = xb_add(&bar[XB_TOP], 1u);
;             const unsigned tg = og / nx;
;             if (og + 1u == (tg + 1u) * nx) xb_add(&bar[XB_TOPGEN], 1u);
;             else XB_SPIN(xb_ld(&bar[XB_TOPGEN]) == tg, bar);
;             __builtin_amdgcn_fence(__ATOMIC_ACQUIRE, "agent");
;             xb_add(&bar[XB_XGEN(b.x)], 1u);
;             asm volatile("s_waitcnt vmcnt(0)" ::: "memory");
;         } else {
;             XB_SPIN(xb_ld(&bar[XB_XGEN(b.x)]) == gen, bar);
;             __builtin_amdgcn_fence(__ATOMIC_ACQUIRE, "agent");
;             asm volatile("s_waitcnt vmcnt(0)" ::: "memory");
;         }
.LBB0_801:
	global_atomic_add v4, v[134:135], v204, off sc0
	v_cvt_f32_u32_e32 v0, v3
	v_sub_u32_e32 v5, 0, v3
	v_rcp_iflag_f32_e32 v0, v0
	s_nop 0
	v_mul_f32_e32 v0, 0x4f7ffffe, v0
	v_cvt_u32_f32_e32 v0, v0
	v_mul_lo_u32 v5, v5, v0
	v_mul_hi_u32 v5, v0, v5
	v_add_u32_e32 v0, v0, v5
	s_waitcnt vmcnt(0)
	v_mul_hi_u32 v0, v4, v0
	v_mul_lo_u32 v5, v0, v3
	v_sub_u32_e32 v5, v4, v5
	v_add_u32_e32 v6, 1, v0
	v_cmp_ge_u32_e32 vcc, v5, v3
	v_add_u32_e32 v4, 1, v4
	s_nop 0
	v_cndmask_b32_e32 v0, v0, v6, vcc
	v_sub_u32_e32 v6, v5, v3
	v_cndmask_b32_e32 v5, v5, v6, vcc
	v_add_u32_e32 v6, 1, v0
	v_cmp_ge_u32_e32 vcc, v5, v3
	s_nop 1
	v_cndmask_b32_e32 v0, v0, v6, vcc
	v_mul_lo_u32 v5, v3, v0
	v_add_u32_e32 v3, v5, v3
	v_cmp_ne_u32_e32 vcc, v4, v3
	s_and_saveexec_b64 s[6:7], vcc
	s_xor_b64 s[16:17], exec, s[6:7]
	s_cbranch_execz .LBB0_815
	s_waitcnt lgkmcnt(0)
	v_readlane_b32 s6, v254, 14
	v_readlane_b32 s7, v254, 15
	s_nop 4
	global_load_dword v2, v1, s[6:7] sc1
	s_waitcnt vmcnt(0)
	v_cmp_eq_u32_e32 vcc, v2, v0
	s_and_saveexec_b64 s[18:19], vcc
	s_cbranch_execz .LBB0_814
	s_mov_b32 s2, 1
	s_mov_b64 s[20:21], 0
	s_branch .LBB0_805

; __device__ __forceinline__ unsigned xb_ld(unsigned* p)              { return __hip_atomic_load(p, __ATOMIC_RELAXED, __HIP_MEMORY_SCOPE_AGENT); }
; #define XB_SPIN(cond, bar) do { unsigned _sp = 0; while (cond) { __builtin_amdgcn_s_sleep(1); \
;     if ((++_sp & 255u) == 0u) { if (xb_ld(&(bar)[XB_TMO])) break; if (_sp > XB_SPIN_CAP) { atomicAdd(&(bar)[XB_TMO], 1u); break; } } } } while (0)
; __device__ __forceinline__ void grid_barrier(const XcdBarrier& b) {
;     ...
;             XB_SPIN(xb_ld(&bar[XB_XGEN(b.x)]) == gen, bar);
.LBB0_809:
	v_readlane_b32 s6, v254, 14
	v_readlane_b32 s7, v254, 15
	s_nop 4
	global_load_dword v2, v1, s[6:7] sc1
	s_add_i32 s2, s2, 1
	s_mov_b64 s[40:41], -1
	s_waitcnt vmcnt(0)
	v_cmp_ne_u32_e32 vcc, v2, v0
	s_orn2_b64 s[38:39], vcc, exec
	s_branch .LBB0_804
